# attention softmax: exponent arguments computed with 8 packed v_pk_fma_f32 per query group instead of 16 scalar fmamk (same fma per element)
# baseline (speedup 1.0000x reference)
.LBB0_571:
	v_mul_f32_e32 v159, 0xbe38aa3b, v146
	s_mov_b32 s98, 0x3e38aa3b
	v_pk_fma_f32 v[118:119], v[118:119], s[98:99], v[158:159] op_sel:[0,0,1] op_sel_hi:[1,0,1]
	v_pk_fma_f32 v[120:121], v[120:121], s[98:99], v[158:159] op_sel:[0,0,1] op_sel_hi:[1,0,1]
	v_pk_fma_f32 v[122:123], v[122:123], s[98:99], v[158:159] op_sel:[0,0,1] op_sel_hi:[1,0,1]
	v_pk_fma_f32 v[124:125], v[124:125], s[98:99], v[158:159] op_sel:[0,0,1] op_sel_hi:[1,0,1]
	v_pk_fma_f32 v[126:127], v[126:127], s[98:99], v[158:159] op_sel:[0,0,1] op_sel_hi:[1,0,1]
	v_pk_fma_f32 v[128:129], v[128:129], s[98:99], v[158:159] op_sel:[0,0,1] op_sel_hi:[1,0,1]
	v_pk_fma_f32 v[130:131], v[130:131], s[98:99], v[158:159] op_sel:[0,0,1] op_sel_hi:[1,0,1]
	v_pk_fma_f32 v[132:133], v[132:133], s[98:99], v[158:159] op_sel:[0,0,1] op_sel_hi:[1,0,1]
	v_exp_f32_e32 v146, v122
	v_exp_f32_e32 v130, v130
	v_exp_f32_e32 v131, v131
	v_exp_f32_e32 v132, v132
	v_exp_f32_e32 v133, v133
	v_exp_f32_e32 v147, v123
	v_exp_f32_e32 v126, v126
	v_exp_f32_e32 v127, v127
	v_exp_f32_e32 v128, v128
	v_exp_f32_e32 v129, v129
	v_exp_f32_e32 v160, v124
	v_exp_f32_e32 v176, v118
	v_exp_f32_e32 v161, v125
	v_exp_f32_e32 v177, v119
	v_exp_f32_e32 v178, v120
	v_exp_f32_e32 v179, v121
	v_pk_add_f32 v[118:119], v[130:131], v[132:133]
	v_pk_add_f32 v[120:121], v[126:127], v[128:129]
	v_pk_add_f32 v[118:119], v[118:119], 0 op_sel_hi:[1,0]
	v_cvt_pk_bf16_f32 v122, v126, v127
	v_pk_add_f32 v[118:119], v[120:121], v[118:119]
	v_pk_add_f32 v[120:121], v[146:147], v[160:161]
	v_cvt_pk_bf16_f32 v123, v128, v129
	v_pk_add_f32 v[118:119], v[120:121], v[118:119]
	v_pk_add_f32 v[120:121], v[176:177], v[178:179]
	v_cvt_pk_bf16_f32 v124, v146, v147
	v_pk_add_f32 v[118:119], v[120:121], v[118:119]
	v_cvt_pk_bf16_f32 v120, v130, v131
	v_pk_add_f32 v[118:119], v[118:119], v[118:119] op_sel:[0,1] op_sel_hi:[1,0]
	v_cvt_pk_bf16_f32 v121, v132, v133
	v_pk_add_f32 v[118:119], v[148:149], v[118:119]
	v_cvt_pk_bf16_f32 v125, v160, v161
	s_waitcnt lgkmcnt(1)
	v_mfma_f32_16x16x32_bf16 v[42:45], v[98:101], v[120:123], v[42:45]
	v_max_f32_e32 v119, v115, v115
	v_cvt_pk_bf16_f32 v126, v176, v177
	v_cvt_pk_bf16_f32 v127, v178, v179
	v_mfma_f32_16x16x32_bf16 v[46:49], v[94:97], v[120:123], v[46:49]
	v_mfma_f32_16x16x32_bf16 v[38:41], v[90:93], v[120:123], v[38:41]
	v_mfma_f32_16x16x32_bf16 v[34:37], v[86:89], v[120:123], v[34:37]
	v_max_f32_e32 v120, v114, v114
	v_max_f32_e32 v119, v120, v119
	v_max3_f32 v120, v117, v110, v111
	v_max3_f32 v121, v112, v113, v106
	v_max3_f32 v119, v119, v116, v120
	v_max3_f32 v120, v107, v108, v109
	v_max3_f32 v122, v102, v103, v104
	v_max3_f32 v119, v119, v121, v120
	v_mfma_f32_16x16x32_bf16 v[42:45], v[82:85], v[124:127], v[42:45]
	v_max3_f32 v119, v119, v122, v105
	v_sub_f32_e32 v120, v119, v151
	v_mul_f32_e32 v120, 0x3e38aa3b, v120
	v_mfma_f32_16x16x32_bf16 v[46:49], v[78:81], v[124:127], v[46:49]
	v_cmp_lt_f32_e32 vcc, s9, v120
	v_mfma_f32_16x16x32_bf16 v[38:41], v[74:77], v[124:127], v[38:41]
	s_waitcnt lgkmcnt(0)
	v_mfma_f32_16x16x32_bf16 v[34:37], v[70:73], v[124:127], v[34:37]
	s_cbranch_vccz .LBB0_573
	v_mbcnt_hi_u32_b32 v120, -1, v203
	v_and_b32_e32 v122, 64, v120
	v_xor_b32_e32 v121, 16, v120
	v_add_u32_e32 v122, 64, v122
	v_cmp_lt_i32_e32 vcc, v121, v122
	s_nop 1
	v_cndmask_b32_e32 v121, v120, v121, vcc
	v_lshlrev_b32_e32 v121, 2, v121
	ds_bpermute_b32 v121, v121, v119
	v_max_f32_e32 v119, v119, v119
	s_waitcnt lgkmcnt(0)
	v_max_f32_e32 v121, v121, v121
	v_max_f32_e32 v119, v119, v121
	v_xor_b32_e32 v121, 32, v120
	v_cmp_lt_i32_e32 vcc, v121, v122
	s_nop 1
	v_cndmask_b32_e32 v120, v120, v121, vcc
	v_lshlrev_b32_e32 v120, 2, v120
	ds_bpermute_b32 v120, v120, v119
	s_waitcnt lgkmcnt(0)
	v_max3_f32 v119, v151, v119, v120
	v_sub_f32_e32 v120, v151, v119
	v_mul_f32_e32 v120, 0x3e38aa3b, v120
	v_exp_f32_e32 v120, v120
	v_mov_b32_e32 v151, v119
	v_mul_f32_e32 v149, v149, v120
	v_pk_mul_f32 v[20:21], v[20:21], v[120:121] op_sel_hi:[1,0]
	v_pk_mul_f32 v[18:19], v[18:19], v[120:121] op_sel_hi:[1,0]
	v_pk_mul_f32 v[24:25], v[24:25], v[120:121] op_sel_hi:[1,0]
	v_pk_mul_f32 v[22:23], v[22:23], v[120:121] op_sel_hi:[1,0]
	v_pk_mul_f32 v[28:29], v[28:29], v[120:121] op_sel_hi:[1,0]
	v_pk_mul_f32 v[26:27], v[26:27], v[120:121] op_sel_hi:[1,0]
	v_pk_mul_f32 v[32:33], v[32:33], v[120:121] op_sel_hi:[1,0]
	v_pk_mul_f32 v[30:31], v[30:31], v[120:121] op_sel_hi:[1,0]
.LBB0_573:
	v_mul_f32_e32 v125, 0xbe38aa3b, v151
	s_mov_b32 s98, 0x3e38aa3b
	v_pk_fma_f32 v[102:103], v[102:103], s[98:99], v[124:125] op_sel:[0,0,1] op_sel_hi:[1,0,1]
	v_pk_fma_f32 v[104:105], v[104:105], s[98:99], v[124:125] op_sel:[0,0,1] op_sel_hi:[1,0,1]
	v_pk_fma_f32 v[106:107], v[106:107], s[98:99], v[124:125] op_sel:[0,0,1] op_sel_hi:[1,0,1]
	v_pk_fma_f32 v[108:109], v[108:109], s[98:99], v[124:125] op_sel:[0,0,1] op_sel_hi:[1,0,1]
	v_pk_fma_f32 v[110:111], v[110:111], s[98:99], v[124:125] op_sel:[0,0,1] op_sel_hi:[1,0,1]
	v_pk_fma_f32 v[112:113], v[112:113], s[98:99], v[124:125] op_sel:[0,0,1] op_sel_hi:[1,0,1]
	v_pk_fma_f32 v[114:115], v[114:115], s[98:99], v[124:125] op_sel:[0,0,1] op_sel_hi:[1,0,1]
	v_pk_fma_f32 v[116:117], v[116:117], s[98:99], v[124:125] op_sel:[0,0,1] op_sel_hi:[1,0,1]
	v_exp_f32_e32 v120, v114
	v_exp_f32_e32 v121, v115
	v_exp_f32_e32 v116, v116
	v_exp_f32_e32 v117, v117
	v_exp_f32_e32 v110, v110
	v_exp_f32_e32 v111, v111
	v_exp_f32_e32 v112, v112
	v_exp_f32_e32 v113, v113
	v_exp_f32_e32 v122, v102
	v_exp_f32_e32 v106, v106
	v_exp_f32_e32 v107, v107
	v_exp_f32_e32 v108, v108
	v_exp_f32_e32 v109, v109
	v_exp_f32_e32 v123, v103
	v_exp_f32_e32 v124, v104
	v_exp_f32_e32 v125, v105
	v_pk_add_f32 v[102:103], v[120:121], v[116:117]
	v_pk_add_f32 v[104:105], v[110:111], v[112:113]
	v_pk_add_f32 v[102:103], v[102:103], 0 op_sel_hi:[1,0]
	v_mov_b32_e32 v119, v149
	v_pk_add_f32 v[102:103], v[104:105], v[102:103]
	v_pk_add_f32 v[104:105], v[106:107], v[108:109]
	v_cvt_pk_bf16_f32 v106, v106, v107
	v_pk_add_f32 v[102:103], v[104:105], v[102:103]
	v_pk_add_f32 v[104:105], v[122:123], v[124:125]
	v_cvt_pk_bf16_f32 v107, v108, v109
	v_pk_add_f32 v[102:103], v[104:105], v[102:103]
	v_cvt_pk_bf16_f32 v104, v110, v111
	v_add_f32_e32 v102, v102, v103
	v_pk_add_f32 v[114:115], v[118:119], v[102:103] op_sel_hi:[1,0]
	v_cvt_pk_bf16_f32 v102, v120, v121
	v_cvt_pk_bf16_f32 v103, v116, v117
	v_cvt_pk_bf16_f32 v105, v112, v113
	v_cvt_pk_bf16_f32 v108, v122, v123
	v_cvt_pk_bf16_f32 v109, v124, v125
	v_mfma_f32_16x16x32_bf16 v[18:21], v[98:101], v[102:105], v[18:21]
	v_readlane_b32 s20, v254, 19
	v_readlane_b32 s21, v254, 20
	v_mov_b64_e32 v[146:147], v[150:151]
	v_mfma_f32_16x16x32_bf16 v[22:25], v[94:97], v[102:105], v[22:25]
	v_lshl_add_u64 v[140:141], s[20:21], 1, v[140:141]
	s_cmp_lg_u32 s15, s18
	v_mfma_f32_16x16x32_bf16 v[26:29], v[90:93], v[102:105], v[26:29]
	s_barrier
	v_mfma_f32_16x16x32_bf16 v[30:33], v[86:89], v[102:105], v[30:33]
	v_mfma_f32_16x16x32_bf16 v[18:21], v[82:85], v[106:109], v[18:21]
	v_mfma_f32_16x16x32_bf16 v[22:25], v[78:81], v[106:109], v[22:25]
	v_mfma_f32_16x16x32_bf16 v[26:29], v[74:77], v[106:109], v[26:29]
	v_mfma_f32_16x16x32_bf16 v[30:33], v[70:73], v[106:109], v[30:33]
	s_cbranch_scc0 .LBB0_575
	v_mov_b32_e32 v119, v115
	v_mov_b64_e32 v[148:149], v[118:119]
	s_mov_b32 s19, s18
	s_branch .LBB0_562

.LBB0_583:
	v_mul_f32_e32 v0, 0xbe38aa3b, v117
	s_mov_b32 s98, 0x3e38aa3b
	v_pk_fma_f32 v[50:51], v[50:51], s[98:99], v[0:1] op_sel_hi:[1,0,0]
	v_pk_fma_f32 v[52:53], v[52:53], s[98:99], v[0:1] op_sel_hi:[1,0,0]
	v_pk_fma_f32 v[54:55], v[54:55], s[98:99], v[0:1] op_sel_hi:[1,0,0]
	v_pk_fma_f32 v[56:57], v[56:57], s[98:99], v[0:1] op_sel_hi:[1,0,0]
	v_pk_fma_f32 v[70:71], v[70:71], s[98:99], v[0:1] op_sel_hi:[1,0,0]
	v_pk_fma_f32 v[72:73], v[72:73], s[98:99], v[0:1] op_sel_hi:[1,0,0]
	v_pk_fma_f32 v[94:95], v[94:95], s[98:99], v[0:1] op_sel_hi:[1,0,0]
	v_pk_fma_f32 v[96:97], v[96:97], s[98:99], v[0:1] op_sel_hi:[1,0,0]
	v_exp_f32_e32 v94, v94
	v_exp_f32_e32 v95, v95
	v_exp_f32_e32 v96, v96
	v_exp_f32_e32 v97, v97
	v_exp_f32_e32 v70, v70
	v_exp_f32_e32 v71, v71
	v_exp_f32_e32 v72, v72
	v_exp_f32_e32 v73, v73
	v_exp_f32_e32 v54, v54
	v_exp_f32_e32 v55, v55
	v_exp_f32_e32 v56, v56
	v_exp_f32_e32 v57, v57
	v_exp_f32_e32 v104, v50
	v_exp_f32_e32 v105, v51
	v_exp_f32_e32 v106, v52
	v_exp_f32_e32 v107, v53
	v_pk_add_f32 v[50:51], v[94:95], v[96:97]
	v_pk_add_f32 v[52:53], v[70:71], v[72:73]
	v_pk_add_f32 v[50:51], v[50:51], 0 op_sel_hi:[1,0]
	s_nop 0
	v_pk_add_f32 v[50:51], v[52:53], v[50:51]
	v_pk_add_f32 v[52:53], v[54:55], v[56:57]
	s_barrier
	v_pk_add_f32 v[50:51], v[52:53], v[50:51]
	v_pk_add_f32 v[52:53], v[104:105], v[106:107]
	s_nop 0
	v_pk_add_f32 v[50:51], v[52:53], v[50:51]
	v_cvt_pk_bf16_f32 v52, v70, v71
	v_add_f32_e32 v0, v50, v51
	v_cvt_pk_bf16_f32 v50, v94, v95
	v_cvt_pk_bf16_f32 v51, v96, v97
	v_cvt_pk_bf16_f32 v53, v72, v73
	ds_read_b128 v[70:73], v153 offset:2304
	v_cvt_pk_bf16_f32 v54, v54, v55
	v_mfma_f32_16x16x32_bf16 v[18:21], v[58:61], v[50:53], v[18:21]
	v_cvt_pk_bf16_f32 v55, v56, v57
	v_cvt_pk_bf16_f32 v56, v104, v105
	v_cvt_pk_bf16_f32 v57, v106, v107
	v_mfma_f32_16x16x32_bf16 v[22:25], v[62:65], v[50:53], v[22:25]
	ds_read_b128 v[62:65], v153 offset:4672
	ds_read_b128 v[58:61], v153 offset:6976
	v_mov_b32_e32 v103, v119
	v_mfma_f32_16x16x32_bf16 v[26:29], v[66:69], v[50:53], v[26:29]
	ds_read_b128 v[66:69], v153
	v_pk_add_f32 v[100:101], v[102:103], v[0:1] op_sel_hi:[1,0]
	v_mov_b64_e32 v[98:99], v[116:117]
	v_mfma_f32_16x16x32_bf16 v[30:33], v[74:77], v[50:53], v[30:33]
	ds_read_b128 v[74:77], v153 offset:64
	ds_read_b128 v[50:53], v153 offset:6912
	v_mfma_f32_16x16x32_bf16 v[18:21], v[78:81], v[54:57], v[18:21]
	ds_read_b128 v[78:81], v153 offset:2368
	v_mfma_f32_16x16x32_bf16 v[22:25], v[82:85], v[54:57], v[22:25]
	v_mfma_f32_16x16x32_bf16 v[26:29], v[86:89], v[54:57], v[26:29]
	v_mfma_f32_16x16x32_bf16 v[30:33], v[90:93], v[54:57], v[30:33]
	ds_read_b128 v[54:57], v153 offset:4608
	s_waitcnt lgkmcnt(4)
	v_mfma_f32_16x16x32_bf16 v[82:85], v[66:69], v[14:17], 0
	s_waitcnt lgkmcnt(3)
	v_mfma_f32_16x16x32_bf16 v[82:85], v[74:77], v[10:13], v[82:85]
	v_mfma_f32_16x16x32_bf16 v[86:89], v[70:73], v[14:17], 0
	s_waitcnt lgkmcnt(1)
	v_mfma_f32_16x16x32_bf16 v[86:89], v[78:81], v[10:13], v[86:89]
	s_nop 4
	v_max_f32_e32 v0, v83, v83
	v_max_f32_e32 v100, v82, v82
	v_max_f32_e32 v0, v100, v0
	s_waitcnt lgkmcnt(0)
	v_mfma_f32_16x16x32_bf16 v[90:93], v[54:57], v[14:17], 0
	v_mfma_f32_16x16x32_bf16 v[90:93], v[62:65], v[10:13], v[90:93]
	v_max3_f32 v100, v85, v86, v87
	v_max3_f32 v0, v0, v84, v100
	v_mfma_f32_16x16x32_bf16 v[14:17], v[50:53], v[14:17], 0
	v_mfma_f32_16x16x32_bf16 v[94:97], v[58:61], v[10:13], v[14:17]
	s_nop 3
	v_max3_f32 v103, v88, v89, v90
	v_max3_f32 v100, v91, v92, v93
	v_max3_f32 v0, v0, v103, v100
	v_mfma_f32_16x16x32_bf16 v[10:13], v[66:69], v[2:5], 0
	ds_read_b128 v[14:17], v153 offset:9280
	v_max3_f32 v104, v94, v95, v96
	v_max3_f32 v0, v0, v104, v97
	v_mfma_f32_16x16x32_bf16 v[66:69], v[74:77], v[6:9], v[10:13]
	v_sub_f32_e32 v100, v0, v98
	v_mul_f32_e32 v100, 0x3e38aa3b, v100
	v_cmp_lt_f32_e32 vcc, s4, v100
	v_mfma_f32_16x16x32_bf16 v[10:13], v[70:73], v[2:5], 0
	v_mfma_f32_16x16x32_bf16 v[70:73], v[78:81], v[6:9], v[10:13]
	v_mfma_f32_16x16x32_bf16 v[10:13], v[54:57], v[2:5], 0
	ds_read_b128 v[54:57], v153 offset:13824
	v_mfma_f32_16x16x32_bf16 v[78:81], v[62:65], v[6:9], v[10:13]
	ds_read_b128 v[62:65], v153 offset:9216
	v_mfma_f32_16x16x32_bf16 v[2:5], v[50:53], v[2:5], 0
	ds_read_b128 v[50:53], v153 offset:16128
	s_nop 2
	ds_read_b128 v[10:13], v153 offset:16192
	v_mfma_f32_16x16x32_bf16 v[74:77], v[58:61], v[6:9], v[2:5]
	ds_read_b128 v[58:61], v153 offset:11520
	ds_read_b128 v[6:9], v153 offset:13888
	s_nop 0
	ds_read_b128 v[2:5], v153 offset:11584
	s_cbranch_vccz .LBB0_585
	v_mbcnt_hi_u32_b32 v100, -1, v203
	v_and_b32_e32 v104, 64, v100
	v_xor_b32_e32 v103, 16, v100
	v_add_u32_e32 v104, 64, v104
	v_cmp_lt_i32_e32 vcc, v103, v104
	s_nop 1
	v_cndmask_b32_e32 v103, v100, v103, vcc
	v_lshlrev_b32_e32 v103, 2, v103
	ds_bpermute_b32 v103, v103, v0
	v_max_f32_e32 v0, v0, v0
	s_waitcnt lgkmcnt(0)
	v_max_f32_e32 v103, v103, v103
	v_max_f32_e32 v0, v0, v103
	v_xor_b32_e32 v103, 32, v100
	v_cmp_lt_i32_e32 vcc, v103, v104
	s_nop 1
	v_cndmask_b32_e32 v100, v100, v103, vcc
	v_lshlrev_b32_e32 v100, 2, v100
	ds_bpermute_b32 v100, v100, v0
	s_waitcnt lgkmcnt(0)
	v_max3_f32 v103, v98, v0, v100
	v_sub_f32_e32 v0, v98, v103
	v_mul_f32_e32 v0, 0x3e38aa3b, v0
	v_exp_f32_e32 v0, v0
	v_mov_b32_e32 v98, v103
	v_mul_f32_e32 v100, v102, v0
	v_pk_mul_f32 v[36:37], v[36:37], v[0:1] op_sel_hi:[1,0]
	v_pk_mul_f32 v[34:35], v[34:35], v[0:1] op_sel_hi:[1,0]
	v_pk_mul_f32 v[40:41], v[40:41], v[0:1] op_sel_hi:[1,0]
	v_pk_mul_f32 v[38:39], v[38:39], v[0:1] op_sel_hi:[1,0]
	v_pk_mul_f32 v[44:45], v[44:45], v[0:1] op_sel_hi:[1,0]
	v_pk_mul_f32 v[42:43], v[42:43], v[0:1] op_sel_hi:[1,0]
	v_pk_mul_f32 v[48:49], v[48:49], v[0:1] op_sel_hi:[1,0]
	v_pk_mul_f32 v[46:47], v[46:47], v[0:1] op_sel_hi:[1,0]
	s_branch .LBB0_586

.LBB0_586:
	v_mul_f32_e32 v0, 0xbe38aa3b, v98
	s_mov_b32 s98, 0x3e38aa3b
	v_pk_fma_f32 v[82:83], v[82:83], s[98:99], v[0:1] op_sel_hi:[1,0,0]
	v_pk_fma_f32 v[84:85], v[84:85], s[98:99], v[0:1] op_sel_hi:[1,0,0]
	v_pk_fma_f32 v[86:87], v[86:87], s[98:99], v[0:1] op_sel_hi:[1,0,0]
	v_pk_fma_f32 v[88:89], v[88:89], s[98:99], v[0:1] op_sel_hi:[1,0,0]
	v_pk_fma_f32 v[90:91], v[90:91], s[98:99], v[0:1] op_sel_hi:[1,0,0]
	v_pk_fma_f32 v[92:93], v[92:93], s[98:99], v[0:1] op_sel_hi:[1,0,0]
	v_pk_fma_f32 v[94:95], v[94:95], s[98:99], v[0:1] op_sel_hi:[1,0,0]
	v_pk_fma_f32 v[96:97], v[96:97], s[98:99], v[0:1] op_sel_hi:[1,0,0]
	v_exp_f32_e32 v82, v82
	v_exp_f32_e32 v83, v83
	v_exp_f32_e32 v84, v84
	v_exp_f32_e32 v85, v85
	v_exp_f32_e32 v86, v86
	v_exp_f32_e32 v87, v87
	v_exp_f32_e32 v88, v88
	v_exp_f32_e32 v89, v89
	v_exp_f32_e32 v90, v90
	v_exp_f32_e32 v91, v91
	v_exp_f32_e32 v92, v92
	v_exp_f32_e32 v93, v93
	v_exp_f32_e32 v94, v94
	v_exp_f32_e32 v95, v95
	v_exp_f32_e32 v96, v96
	v_exp_f32_e32 v97, v97
	v_pk_add_f32 v[102:103], v[82:83], v[84:85]
	v_cvt_pk_bf16_f32 v82, v82, v83
	v_cvt_pk_bf16_f32 v83, v84, v85
	v_cvt_pk_bf16_f32 v84, v86, v87
	v_cvt_pk_bf16_f32 v85, v88, v89
	v_max_f32_e32 v0, v67, v67
	v_pk_add_f32 v[102:103], v[102:103], 0 op_sel_hi:[1,0]
	s_waitcnt lgkmcnt(5)
	v_mfma_f32_16x16x32_bf16 v[34:37], v[62:65], v[82:85], v[34:37]
	v_add_f32_e64 v104, v86, v88
	v_add_f32_e64 v105, v87, v89
	v_cvt_pk_bf16_f32 v86, v90, v91
	v_pk_add_f32 v[102:103], v[104:105], v[102:103]
	s_waitcnt lgkmcnt(2)
	v_mfma_f32_16x16x32_bf16 v[38:41], v[58:61], v[82:85], v[38:41]
	v_add_f32_e64 v104, v90, v92
	v_add_f32_e64 v105, v91, v93
	v_cvt_pk_bf16_f32 v87, v92, v93
	v_cvt_pk_bf16_f32 v88, v94, v95
	v_mfma_f32_16x16x32_bf16 v[42:45], v[54:57], v[82:85], v[42:45]
	v_cvt_pk_bf16_f32 v89, v96, v97
	v_pk_add_f32 v[102:103], v[104:105], v[102:103]
	v_pk_add_f32 v[104:105], v[94:95], v[96:97]
	v_mfma_f32_16x16x32_bf16 v[46:49], v[50:53], v[82:85], v[46:49]
	v_max_f32_e32 v82, v66, v66
	v_max_f32_e32 v0, v82, v0
	v_max3_f32 v82, v69, v70, v71
	v_max3_f32 v83, v72, v73, v78
	v_max3_f32 v0, v0, v68, v82
	v_max3_f32 v82, v79, v80, v81
	v_max3_f32 v84, v74, v75, v76
	v_max3_f32 v0, v0, v83, v82
	v_mfma_f32_16x16x32_bf16 v[34:37], v[14:17], v[86:89], v[34:37]
	v_max3_f32 v82, v0, v84, v77
	v_pk_add_f32 v[102:103], v[104:105], v[102:103]
	v_sub_f32_e32 v0, v82, v99
	s_waitcnt lgkmcnt(0)
	v_mfma_f32_16x16x32_bf16 v[38:41], v[2:5], v[86:89], v[38:41]
	v_pk_add_f32 v[102:103], v[102:103], v[102:103] op_sel:[0,1] op_sel_hi:[1,0]
	v_mul_f32_e32 v0, 0x3e38aa3b, v0
	v_pk_add_f32 v[102:103], v[100:101], v[102:103]
	v_mfma_f32_16x16x32_bf16 v[42:45], v[6:9], v[86:89], v[42:45]
	v_cmp_lt_f32_e32 vcc, s4, v0
	v_mfma_f32_16x16x32_bf16 v[46:49], v[10:13], v[86:89], v[46:49]
	s_cbranch_vccz .LBB0_634
	v_mbcnt_hi_u32_b32 v0, -1, v203
	v_and_b32_e32 v83, 64, v0
	v_xor_b32_e32 v98, 16, v0
	v_add_u32_e32 v100, 64, v83
	v_cmp_lt_i32_e32 vcc, v98, v100
	v_xor_b32_e32 v103, 32, v0
	s_nop 0
	v_cndmask_b32_e32 v83, v0, v98, vcc
	v_lshlrev_b32_e32 v83, 2, v83
	ds_bpermute_b32 v83, v83, v82
	v_max_f32_e32 v82, v82, v82
	v_cmp_lt_i32_e32 vcc, v103, v100
	s_waitcnt lgkmcnt(0)
	v_max_f32_e32 v83, v83, v83
	v_max_f32_e32 v82, v82, v83
	v_cndmask_b32_e32 v83, v0, v103, vcc
	v_lshlrev_b32_e32 v83, 2, v83
	ds_bpermute_b32 v83, v83, v82
	s_waitcnt lgkmcnt(0)
	v_max3_f32 v105, v99, v82, v83
	v_sub_f32_e32 v82, v99, v105
	v_mul_f32_e32 v82, 0x3e38aa3b, v82
	v_exp_f32_e32 v82, v82
	s_nop 0
	v_mul_f32_e32 v104, v101, v82
	v_pk_mul_f32 v[96:97], v[20:21], v[82:83] op_sel_hi:[1,0]
	v_pk_mul_f32 v[94:95], v[18:19], v[82:83] op_sel_hi:[1,0]
	v_pk_mul_f32 v[92:93], v[24:25], v[82:83] op_sel_hi:[1,0]
	v_pk_mul_f32 v[90:91], v[22:23], v[82:83] op_sel_hi:[1,0]
	v_pk_mul_f32 v[88:89], v[28:29], v[82:83] op_sel_hi:[1,0]
	v_pk_mul_f32 v[86:87], v[26:27], v[82:83] op_sel_hi:[1,0]
	v_pk_mul_f32 v[84:85], v[32:33], v[82:83] op_sel_hi:[1,0]
	v_pk_mul_f32 v[82:83], v[30:31], v[82:83] op_sel_hi:[1,0]
	s_cbranch_execnz .LBB0_589

.LBB0_589:
	v_mul_f32_e32 v33, 0xbe38aa3b, v105
	s_mov_b32 s98, 0x3e38aa3b
	v_pk_fma_f32 v[66:67], v[66:67], s[98:99], v[32:33] op_sel:[0,0,1] op_sel_hi:[1,0,1]
	v_pk_fma_f32 v[68:69], v[68:69], s[98:99], v[32:33] op_sel:[0,0,1] op_sel_hi:[1,0,1]
	v_pk_fma_f32 v[70:71], v[70:71], s[98:99], v[32:33] op_sel:[0,0,1] op_sel_hi:[1,0,1]
	v_pk_fma_f32 v[72:73], v[72:73], s[98:99], v[32:33] op_sel:[0,0,1] op_sel_hi:[1,0,1]
	v_pk_fma_f32 v[74:75], v[74:75], s[98:99], v[32:33] op_sel:[0,0,1] op_sel_hi:[1,0,1]
	v_pk_fma_f32 v[76:77], v[76:77], s[98:99], v[32:33] op_sel:[0,0,1] op_sel_hi:[1,0,1]
	v_pk_fma_f32 v[78:79], v[78:79], s[98:99], v[32:33] op_sel:[0,0,1] op_sel_hi:[1,0,1]
	v_pk_fma_f32 v[80:81], v[80:81], s[98:99], v[32:33] op_sel:[0,0,1] op_sel_hi:[1,0,1]
	v_exp_f32_e32 v18, v66
	v_exp_f32_e32 v19, v67
	v_exp_f32_e32 v20, v68
	v_exp_f32_e32 v21, v69
	v_exp_f32_e32 v22, v70
	v_exp_f32_e32 v23, v71
	v_exp_f32_e32 v24, v72
	v_exp_f32_e32 v25, v73
	v_exp_f32_e32 v26, v78
	v_exp_f32_e32 v27, v79
	v_exp_f32_e32 v28, v80
	v_exp_f32_e32 v29, v81
	v_exp_f32_e32 v30, v74
	v_exp_f32_e32 v31, v75
	v_exp_f32_e32 v32, v76
	v_exp_f32_e32 v33, v77
	v_pk_add_f32 v[66:67], v[18:19], v[20:21]
	v_pk_add_f32 v[68:69], v[22:23], v[24:25]
	v_pk_add_f32 v[66:67], v[66:67], 0 op_sel_hi:[1,0]
	v_cvt_pk_bf16_f32 v18, v18, v19
	v_pk_add_f32 v[66:67], v[68:69], v[66:67]
	v_pk_add_f32 v[68:69], v[26:27], v[28:29]
	v_cvt_pk_bf16_f32 v19, v20, v21
	v_cvt_pk_bf16_f32 v20, v22, v23
	v_cvt_pk_bf16_f32 v21, v24, v25
	v_pk_add_f32 v[66:67], v[68:69], v[66:67]
	v_pk_add_f32 v[68:69], v[30:31], v[32:33]
	v_cvt_pk_bf16_f32 v24, v30, v31
	v_cvt_pk_bf16_f32 v25, v32, v33
	v_mfma_f32_16x16x32_bf16 v[30:33], v[58:61], v[18:21], v[90:93]
	v_cvt_pk_bf16_f32 v22, v26, v27
	v_cvt_pk_bf16_f32 v23, v28, v29
	v_cmp_lt_i32_e32 vcc, v98, v100
	v_mfma_f32_16x16x32_bf16 v[50:53], v[50:53], v[18:21], v[82:85]
	s_lshl_b64 s[4:5], s[10:11], 11
	v_readlane_b32 s8, v254, 33
	v_readlane_b32 s9, v254, 34
	v_mfma_f32_16x16x32_bf16 v[26:29], v[62:65], v[18:21], v[94:97]
	s_add_u32 s4, s8, s4
	s_addc_u32 s5, s9, s5
	s_lshl_b32 s7, s7, 1
	v_mfma_f32_16x16x32_bf16 v[54:57], v[54:57], v[18:21], v[86:89]
	s_add_u32 s4, s4, s7
	s_addc_u32 s5, s5, 0
	v_mfma_f32_16x16x32_bf16 v[18:21], v[2:5], v[22:25], v[30:33]
	s_barrier
	v_pk_add_f32 v[66:67], v[68:69], v[66:67]
	v_mfma_f32_16x16x32_bf16 v[2:5], v[10:13], v[22:25], v[50:53]
	v_cndmask_b32_e32 v10, v0, v98, vcc
	v_cmp_lt_i32_e32 vcc, v103, v100
	v_add_f32_e32 v66, v66, v67
	v_mfma_f32_16x16x32_bf16 v[14:17], v[14:17], v[22:25], v[26:29]
	v_cndmask_b32_e32 v0, v0, v103, vcc
	v_add_f32_e32 v66, v104, v66
	s_nop 0
	v_lshlrev_b32_e32 v26, 2, v10
	v_lshlrev_b32_e32 v27, 2, v0
	ds_bpermute_b32 v0, v26, v102
	v_mfma_f32_16x16x32_bf16 v[6:9], v[6:9], v[22:25], v[54:57]
	s_waitcnt lgkmcnt(0)
	v_add_f32_e32 v0, v102, v0
	ds_bpermute_b32 v10, v27, v0
	s_waitcnt lgkmcnt(0)
	v_add_f32_e32 v0, v0, v10
	v_div_scale_f32 v10, s[8:9], v0, v0, 1.0
	v_rcp_f32_e32 v11, v10
	s_nop 0
	v_fma_f32 v12, -v10, v11, 1.0
	v_fmac_f32_e32 v11, v12, v11
	v_div_scale_f32 v12, vcc, 1.0, v0, 1.0
	v_mul_f32_e32 v13, v12, v11
	v_fma_f32 v22, -v10, v13, v12
	v_fmac_f32_e32 v13, v22, v11
	v_fma_f32 v10, -v10, v13, v12
	v_div_fmas_f32 v10, v10, v11, v13
	v_div_fixup_f32 v10, v10, v0, 1.0
	v_lshlrev_b64 v[12:13], 11, v[136:137]
	v_lshl_add_u64 v[12:13], s[4:5], 0, v[12:13]
	v_lshlrev_b32_e32 v0, 3, v152
	v_pk_mul_f32 v[22:23], v[36:37], v[10:11] op_sel_hi:[1,0]
	v_pk_mul_f32 v[24:25], v[34:35], v[10:11] op_sel_hi:[1,0]
	v_lshl_add_u64 v[12:13], v[12:13], 0, v[0:1]
	v_cvt_pk_bf16_f32 v24, v24, v25
	v_cvt_pk_bf16_f32 v25, v22, v23
	global_store_dwordx2 v[12:13], v[24:25], off offset:1536
	v_pk_mul_f32 v[22:23], v[40:41], v[10:11] op_sel_hi:[1,0]
	v_pk_mul_f32 v[24:25], v[38:39], v[10:11] op_sel_hi:[1,0]
	s_nop 0
	v_cvt_pk_bf16_f32 v24, v24, v25
	v_cvt_pk_bf16_f32 v25, v22, v23
	global_store_dwordx2 v[12:13], v[24:25], off offset:1568
	v_pk_mul_f32 v[22:23], v[44:45], v[10:11] op_sel_hi:[1,0]
	v_pk_mul_f32 v[24:25], v[42:43], v[10:11] op_sel_hi:[1,0]
	s_nop 0
	v_cvt_pk_bf16_f32 v24, v24, v25
	v_cvt_pk_bf16_f32 v25, v22, v23
	v_pk_mul_f32 v[22:23], v[48:49], v[10:11] op_sel_hi:[1,0]
	v_pk_mul_f32 v[10:11], v[46:47], v[10:11] op_sel_hi:[1,0]
	global_store_dwordx2 v[12:13], v[24:25], off offset:1600
	v_cvt_pk_bf16_f32 v10, v10, v11
	v_cvt_pk_bf16_f32 v11, v22, v23
	global_store_dwordx2 v[12:13], v[10:11], off offset:1632
	ds_bpermute_b32 v10, v26, v66
	s_waitcnt lgkmcnt(0)
	v_add_f32_e32 v10, v66, v10
	ds_bpermute_b32 v11, v27, v10
	s_waitcnt lgkmcnt(0)
	v_add_f32_e32 v10, v10, v11
	v_div_scale_f32 v11, s[8:9], v10, v10, 1.0
	v_rcp_f32_e32 v12, v11
	s_nop 0
	v_fma_f32 v13, -v11, v12, 1.0
	v_fmac_f32_e32 v12, v13, v12
	v_div_scale_f32 v13, vcc, 1.0, v10, 1.0
	v_mul_f32_e32 v22, v13, v12
	v_fma_f32 v23, -v11, v22, v13
	v_fmac_f32_e32 v22, v23, v12
	v_fma_f32 v11, -v11, v22, v13
	v_div_fmas_f32 v11, v11, v12, v22
	v_div_fixup_f32 v10, v11, v10, 1.0
	v_lshlrev_b64 v[12:13], 11, v[134:135]
	v_lshl_add_u64 v[12:13], s[4:5], 0, v[12:13]
	v_pk_mul_f32 v[16:17], v[16:17], v[10:11] op_sel_hi:[1,0]
	v_pk_mul_f32 v[14:15], v[14:15], v[10:11] op_sel_hi:[1,0]
	v_lshl_add_u64 v[12:13], v[12:13], 0, v[0:1]
	v_cvt_pk_bf16_f32 v14, v14, v15
	v_cvt_pk_bf16_f32 v15, v16, v17
	global_store_dwordx2 v[12:13], v[14:15], off offset:1536
	v_pk_mul_f32 v[14:15], v[20:21], v[10:11] op_sel_hi:[1,0]
	v_pk_mul_f32 v[16:17], v[18:19], v[10:11] op_sel_hi:[1,0]
	v_pk_mul_f32 v[8:9], v[8:9], v[10:11] op_sel_hi:[1,0]
	v_pk_mul_f32 v[6:7], v[6:7], v[10:11] op_sel_hi:[1,0]
	v_pk_mul_f32 v[4:5], v[4:5], v[10:11] op_sel_hi:[1,0]
	v_pk_mul_f32 v[2:3], v[2:3], v[10:11] op_sel_hi:[1,0]
	v_cvt_pk_bf16_f32 v16, v16, v17
	v_cvt_pk_bf16_f32 v17, v14, v15
	v_cvt_pk_bf16_f32 v6, v6, v7
	v_cvt_pk_bf16_f32 v7, v8, v9
	v_cvt_pk_bf16_f32 v2, v2, v3
	v_cvt_pk_bf16_f32 v3, v4, v5
	global_store_dwordx2 v[12:13], v[16:17], off offset:1568
	global_store_dwordx2 v[12:13], v[6:7], off offset:1600
	global_store_dwordx2 v[12:13], v[2:3], off offset:1632
	s_branch .LBB0_645

.LBB0_624:
	v_mul_f32_e32 v153, 0xbe16c740, v160
	s_mov_b32 s98, 0x3e16c740
	v_pk_fma_f32 v[130:131], v[130:131], s[98:99], v[152:153] op_sel:[0,0,1] op_sel_hi:[1,0,1]
	v_pk_fma_f32 v[132:133], v[132:133], s[98:99], v[152:153] op_sel:[0,0,1] op_sel_hi:[1,0,1]
	v_pk_fma_f32 v[134:135], v[134:135], s[98:99], v[152:153] op_sel:[0,0,1] op_sel_hi:[1,0,1]
	v_pk_fma_f32 v[136:137], v[136:137], s[98:99], v[152:153] op_sel:[0,0,1] op_sel_hi:[1,0,1]
	v_pk_fma_f32 v[138:139], v[138:139], s[98:99], v[152:153] op_sel:[0,0,1] op_sel_hi:[1,0,1]
	v_pk_fma_f32 v[140:141], v[140:141], s[98:99], v[152:153] op_sel:[0,0,1] op_sel_hi:[1,0,1]
	v_pk_fma_f32 v[142:143], v[142:143], s[98:99], v[152:153] op_sel:[0,0,1] op_sel_hi:[1,0,1]
	v_pk_fma_f32 v[144:145], v[144:145], s[98:99], v[152:153] op_sel:[0,0,1] op_sel_hi:[1,0,1]
	v_exp_f32_e32 v160, v130
	v_exp_f32_e32 v161, v131
	v_exp_f32_e32 v196, v132
	v_exp_f32_e32 v197, v133
	v_exp_f32_e32 v134, v134
	v_exp_f32_e32 v135, v135
	v_exp_f32_e32 v136, v136
	v_exp_f32_e32 v137, v137
	v_exp_f32_e32 v138, v138
	v_exp_f32_e32 v139, v139
	v_exp_f32_e32 v140, v140
	v_exp_f32_e32 v141, v141
	v_exp_f32_e32 v142, v142
	v_exp_f32_e32 v143, v143
	v_exp_f32_e32 v144, v144
	v_exp_f32_e32 v145, v145
	v_pk_add_f32 v[130:131], v[160:161], v[196:197]
	v_pk_add_f32 v[132:133], v[134:135], v[136:137]
	v_pk_add_f32 v[130:131], v[130:131], 0 op_sel_hi:[1,0]
	v_cvt_pk_bf16_f32 v134, v134, v135
	v_pk_add_f32 v[130:131], v[132:133], v[130:131]
	v_pk_add_f32 v[132:133], v[138:139], v[140:141]
	v_cvt_pk_bf16_f32 v135, v136, v137
	v_pk_add_f32 v[130:131], v[132:133], v[130:131]
	v_pk_add_f32 v[132:133], v[142:143], v[144:145]
	v_cvt_pk_bf16_f32 v136, v138, v139
	v_pk_add_f32 v[130:131], v[132:133], v[130:131]
	v_cvt_pk_bf16_f32 v132, v160, v161
	v_pk_add_f32 v[130:131], v[130:131], v[130:131] op_sel:[0,1] op_sel_hi:[1,0]
	v_cvt_pk_bf16_f32 v133, v196, v197
	v_pk_add_f32 v[130:131], v[182:183], v[130:131]
	v_cvt_pk_bf16_f32 v137, v140, v141
	s_waitcnt lgkmcnt(7)
	v_mfma_f32_16x16x32_bf16 v[54:57], v[110:113], v[132:135], v[54:57]
	v_max_f32_e32 v131, v127, v127
	v_cvt_pk_bf16_f32 v138, v142, v143
	v_cvt_pk_bf16_f32 v139, v144, v145
	s_waitcnt lgkmcnt(6)
	v_mfma_f32_16x16x32_bf16 v[50:53], v[106:109], v[132:135], v[50:53]
	s_waitcnt lgkmcnt(5)
	v_mfma_f32_16x16x32_bf16 v[46:49], v[102:105], v[132:135], v[46:49]
	s_waitcnt lgkmcnt(4)
	v_mfma_f32_16x16x32_bf16 v[42:45], v[98:101], v[132:135], v[42:45]
	v_max_f32_e32 v132, v126, v126
	v_max_f32_e32 v131, v132, v131
	v_max3_f32 v132, v129, v122, v123
	v_max3_f32 v133, v124, v125, v118
	v_max3_f32 v131, v131, v128, v132
	v_max3_f32 v132, v119, v120, v121
	v_max3_f32 v134, v114, v115, v116
	v_max3_f32 v131, v131, v133, v132
	s_waitcnt lgkmcnt(3)
	v_mfma_f32_16x16x32_bf16 v[54:57], v[94:97], v[136:139], v[54:57]
	v_max3_f32 v131, v131, v134, v117
	v_sub_f32_e32 v132, v131, v185
	v_mul_f32_e32 v132, 0x3e16c740, v132
	s_waitcnt lgkmcnt(2)
	v_mfma_f32_16x16x32_bf16 v[50:53], v[90:93], v[136:139], v[50:53]
	v_cmp_lt_f32_e32 vcc, s8, v132
	s_waitcnt lgkmcnt(1)
	v_mfma_f32_16x16x32_bf16 v[46:49], v[86:89], v[136:139], v[46:49]
	s_waitcnt lgkmcnt(0)
	v_mfma_f32_16x16x32_bf16 v[42:45], v[82:85], v[136:139], v[42:45]
	s_cbranch_vccz .LBB0_626
	v_mbcnt_hi_u32_b32 v132, -1, v203
	v_and_b32_e32 v134, 64, v132
	v_xor_b32_e32 v133, 16, v132
	v_add_u32_e32 v134, 64, v134
	v_cmp_lt_i32_e32 vcc, v133, v134
	s_nop 1
	v_cndmask_b32_e32 v133, v132, v133, vcc
	v_lshlrev_b32_e32 v133, 2, v133
	ds_bpermute_b32 v133, v133, v131
	v_max_f32_e32 v131, v131, v131
	s_waitcnt lgkmcnt(0)
	v_max_f32_e32 v133, v133, v133
	v_max_f32_e32 v131, v131, v133
	v_xor_b32_e32 v133, 32, v132
	v_cmp_lt_i32_e32 vcc, v133, v134
	s_nop 1
	v_cndmask_b32_e32 v132, v132, v133, vcc
	v_lshlrev_b32_e32 v132, 2, v132
	ds_bpermute_b32 v132, v132, v131
	s_waitcnt lgkmcnt(0)
	v_max3_f32 v131, v185, v131, v132
	v_sub_f32_e32 v132, v185, v131
	v_mul_f32_e32 v132, 0x3e16c740, v132
	v_exp_f32_e32 v132, v132
	v_mov_b32_e32 v185, v131
	v_mul_f32_e32 v183, v183, v132
	v_pk_mul_f32 v[28:29], v[28:29], v[132:133] op_sel_hi:[1,0]
	v_pk_mul_f32 v[26:27], v[26:27], v[132:133] op_sel_hi:[1,0]
	v_pk_mul_f32 v[32:33], v[32:33], v[132:133] op_sel_hi:[1,0]
	v_pk_mul_f32 v[30:31], v[30:31], v[132:133] op_sel_hi:[1,0]
	v_pk_mul_f32 v[36:37], v[36:37], v[132:133] op_sel_hi:[1,0]
	v_pk_mul_f32 v[34:35], v[34:35], v[132:133] op_sel_hi:[1,0]
	v_pk_mul_f32 v[40:41], v[40:41], v[132:133] op_sel_hi:[1,0]
	v_pk_mul_f32 v[38:39], v[38:39], v[132:133] op_sel_hi:[1,0]
.LBB0_626:
	v_mul_f32_e32 v137, 0xbe16c740, v185
	s_mov_b32 s98, 0x3e16c740
	v_pk_fma_f32 v[114:115], v[114:115], s[98:99], v[136:137] op_sel:[0,0,1] op_sel_hi:[1,0,1]
	v_pk_fma_f32 v[116:117], v[116:117], s[98:99], v[136:137] op_sel:[0,0,1] op_sel_hi:[1,0,1]
	v_pk_fma_f32 v[118:119], v[118:119], s[98:99], v[136:137] op_sel:[0,0,1] op_sel_hi:[1,0,1]
	v_pk_fma_f32 v[120:121], v[120:121], s[98:99], v[136:137] op_sel:[0,0,1] op_sel_hi:[1,0,1]
	v_pk_fma_f32 v[122:123], v[122:123], s[98:99], v[136:137] op_sel:[0,0,1] op_sel_hi:[1,0,1]
	v_pk_fma_f32 v[124:125], v[124:125], s[98:99], v[136:137] op_sel:[0,0,1] op_sel_hi:[1,0,1]
	v_pk_fma_f32 v[126:127], v[126:127], s[98:99], v[136:137] op_sel:[0,0,1] op_sel_hi:[1,0,1]
	v_pk_fma_f32 v[128:129], v[128:129], s[98:99], v[136:137] op_sel:[0,0,1] op_sel_hi:[1,0,1]
	v_exp_f32_e32 v132, v122
	v_exp_f32_e32 v133, v123
	v_exp_f32_e32 v126, v126
	v_exp_f32_e32 v127, v127
	v_exp_f32_e32 v128, v128
	v_exp_f32_e32 v129, v129
	v_exp_f32_e32 v124, v124
	v_exp_f32_e32 v125, v125
	v_exp_f32_e32 v134, v114
	v_exp_f32_e32 v118, v118
	v_exp_f32_e32 v119, v119
	v_exp_f32_e32 v120, v120
	v_exp_f32_e32 v121, v121
	v_exp_f32_e32 v135, v115
	v_exp_f32_e32 v136, v116
	v_exp_f32_e32 v137, v117
	v_pk_add_f32 v[114:115], v[126:127], v[128:129]
	v_pk_add_f32 v[116:117], v[132:133], v[124:125]
	v_pk_add_f32 v[114:115], v[114:115], 0 op_sel_hi:[1,0]
	v_mov_b32_e32 v131, v183
	v_pk_add_f32 v[114:115], v[116:117], v[114:115]
	v_pk_add_f32 v[116:117], v[118:119], v[120:121]
	v_cvt_pk_bf16_f32 v118, v118, v119
	v_pk_add_f32 v[114:115], v[116:117], v[114:115]
	v_pk_add_f32 v[116:117], v[134:135], v[136:137]
	v_cvt_pk_bf16_f32 v119, v120, v121
	v_pk_add_f32 v[114:115], v[116:117], v[114:115]
	v_cvt_pk_bf16_f32 v116, v132, v133
	v_add_f32_e32 v114, v114, v115
	v_pk_add_f32 v[122:123], v[130:131], v[114:115] op_sel_hi:[1,0]
	v_cvt_pk_bf16_f32 v114, v126, v127
	v_cvt_pk_bf16_f32 v115, v128, v129
	v_cvt_pk_bf16_f32 v117, v124, v125
	v_cvt_pk_bf16_f32 v120, v134, v135
	v_cvt_pk_bf16_f32 v121, v136, v137
	v_mfma_f32_16x16x32_bf16 v[26:29], v[110:113], v[114:117], v[26:29]
	v_mov_b64_e32 v[160:161], v[184:185]
	v_lshl_add_u64 v[158:159], v[0:1], 1, v[158:159]
	s_cmp_lg_u32 s0, s13
	v_mfma_f32_16x16x32_bf16 v[30:33], v[106:109], v[114:117], v[30:33]
	s_barrier
	v_mfma_f32_16x16x32_bf16 v[34:37], v[102:105], v[114:117], v[34:37]
	v_mfma_f32_16x16x32_bf16 v[38:41], v[98:101], v[114:117], v[38:41]
	v_mfma_f32_16x16x32_bf16 v[26:29], v[94:97], v[118:121], v[26:29]
	v_mfma_f32_16x16x32_bf16 v[30:33], v[90:93], v[118:121], v[30:33]
	v_mfma_f32_16x16x32_bf16 v[34:37], v[86:89], v[118:121], v[34:37]
	v_mfma_f32_16x16x32_bf16 v[38:41], v[82:85], v[118:121], v[38:41]
	s_cbranch_scc0 .LBB0_628
	v_mov_b32_e32 v131, v123
	v_mov_b64_e32 v[182:183], v[130:131]
	s_mov_b32 s14, s13
	s_branch .LBB0_611

.LBB0_638:
	v_mul_f32_e32 v0, 0xbe16c740, v125
	s_mov_b32 s98, 0x3e16c740
	v_pk_fma_f32 v[58:59], v[58:59], s[98:99], v[0:1] op_sel_hi:[1,0,0]
	v_pk_fma_f32 v[60:61], v[60:61], s[98:99], v[0:1] op_sel_hi:[1,0,0]
	v_pk_fma_f32 v[62:63], v[62:63], s[98:99], v[0:1] op_sel_hi:[1,0,0]
	v_pk_fma_f32 v[64:65], v[64:65], s[98:99], v[0:1] op_sel_hi:[1,0,0]
	v_pk_fma_f32 v[66:67], v[66:67], s[98:99], v[0:1] op_sel_hi:[1,0,0]
	v_pk_fma_f32 v[68:69], v[68:69], s[98:99], v[0:1] op_sel_hi:[1,0,0]
	v_pk_fma_f32 v[70:71], v[70:71], s[98:99], v[0:1] op_sel_hi:[1,0,0]
	v_pk_fma_f32 v[72:73], v[72:73], s[98:99], v[0:1] op_sel_hi:[1,0,0]
	v_exp_f32_e32 v70, v70
	v_exp_f32_e32 v71, v71
	v_exp_f32_e32 v72, v72
	v_exp_f32_e32 v73, v73
	v_exp_f32_e32 v66, v66
	v_exp_f32_e32 v67, v67
	v_exp_f32_e32 v68, v68
	v_exp_f32_e32 v69, v69
	v_exp_f32_e32 v62, v62
	v_exp_f32_e32 v63, v63
	v_exp_f32_e32 v64, v64
	v_exp_f32_e32 v65, v65
	v_exp_f32_e32 v106, v58
	v_exp_f32_e32 v107, v59
	v_exp_f32_e32 v108, v60
	v_exp_f32_e32 v109, v61
	v_pk_add_f32 v[58:59], v[70:71], v[72:73]
	v_pk_add_f32 v[60:61], v[66:67], v[68:69]
	v_pk_add_f32 v[58:59], v[58:59], 0 op_sel_hi:[1,0]
	v_mov_b32_e32 v127, v131
	v_pk_add_f32 v[58:59], v[60:61], v[58:59]
	v_pk_add_f32 v[60:61], v[62:63], v[64:65]
	v_mov_b64_e32 v[122:123], v[124:125]
	v_pk_add_f32 v[58:59], v[60:61], v[58:59]
	v_pk_add_f32 v[60:61], v[106:107], v[108:109]
	s_nop 0
	v_pk_add_f32 v[58:59], v[60:61], v[58:59]
	v_cvt_pk_bf16_f32 v60, v66, v67
	v_add_f32_e32 v0, v58, v59
	v_pk_add_f32 v[124:125], v[126:127], v[0:1] op_sel_hi:[1,0]
	v_cvt_pk_bf16_f32 v58, v70, v71
	v_cvt_pk_bf16_f32 v59, v72, v73
	v_cvt_pk_bf16_f32 v61, v68, v69
	v_add_u32_e32 v0, 0, v150
	s_barrier
	v_mfma_f32_16x16x32_bf16 v[26:29], v[74:77], v[58:61], v[26:29]
	v_cvt_pk_bf16_f32 v62, v62, v63
	v_cvt_pk_bf16_f32 v63, v64, v65
	v_mfma_f32_16x16x32_bf16 v[30:33], v[78:81], v[58:61], v[30:33]
	v_cvt_pk_bf16_f32 v64, v106, v107
	v_cvt_pk_bf16_f32 v65, v108, v109
	v_mfma_f32_16x16x32_bf16 v[34:37], v[82:85], v[58:61], v[34:37]
	v_add_u32_e32 v82, v0, v187
	ds_read_b128 v[114:117], v82 offset:22528
	ds_read_b128 v[118:121], v82 offset:22592
	v_mfma_f32_16x16x32_bf16 v[38:41], v[86:89], v[58:61], v[38:41]
	ds_read_b128 v[66:69], v82 offset:25856
	ds_read_b128 v[74:77], v82 offset:22656
	ds_read_b128 v[58:61], v82 offset:32512
	v_mfma_f32_16x16x32_bf16 v[26:29], v[90:93], v[62:65], v[26:29]
	ds_read_b128 v[78:81], v82 offset:25920
	ds_read_b128 v[70:73], v82 offset:29248
	ds_read_b128 v[110:113], v82 offset:25984
	v_mfma_f32_16x16x32_bf16 v[30:33], v[94:97], v[62:65], v[30:33]
	ds_read_b128 v[106:109], v82 offset:29312
	v_add_u32_e32 v0, v0, v151
	v_mfma_f32_16x16x32_bf16 v[34:37], v[98:101], v[62:65], v[34:37]
	ds_read_b128 v[98:101], v82 offset:32576
	v_mfma_f32_16x16x32_bf16 v[38:41], v[102:105], v[62:65], v[38:41]
	ds_read_b128 v[62:65], v82 offset:29184
	ds_read_b128 v[102:105], v82 offset:32640
	s_waitcnt lgkmcnt(11)
	v_mfma_f32_16x16x32_bf16 v[82:85], v[114:117], v[22:25], 0
	s_waitcnt lgkmcnt(10)
	v_mfma_f32_16x16x32_bf16 v[82:85], v[118:121], v[18:21], v[82:85]
	s_waitcnt lgkmcnt(8)
	v_mfma_f32_16x16x32_bf16 v[82:85], v[74:77], v[14:17], v[82:85]
	v_mfma_f32_16x16x32_bf16 v[86:89], v[66:69], v[22:25], 0
	s_waitcnt lgkmcnt(6)
	v_mfma_f32_16x16x32_bf16 v[86:89], v[78:81], v[18:21], v[86:89]
	s_waitcnt lgkmcnt(4)
	v_mfma_f32_16x16x32_bf16 v[86:89], v[110:113], v[14:17], v[86:89]
	s_waitcnt lgkmcnt(1)
	v_mfma_f32_16x16x32_bf16 v[90:93], v[62:65], v[22:25], 0
	v_mfma_f32_16x16x32_bf16 v[90:93], v[70:73], v[18:21], v[90:93]
	v_mfma_f32_16x16x32_bf16 v[90:93], v[106:109], v[14:17], v[90:93]
	v_mfma_f32_16x16x32_bf16 v[22:25], v[58:61], v[22:25], 0
	v_mfma_f32_16x16x32_bf16 v[18:21], v[98:101], v[18:21], v[22:25]
	s_waitcnt lgkmcnt(0)
	v_mfma_f32_16x16x32_bf16 v[94:97], v[102:105], v[14:17], v[18:21]
	s_nop 4
	ds_read_b128 v[22:25], v0 offset:40448
	v_mfma_f32_16x16x32_bf16 v[14:17], v[114:117], v[2:5], 0
	ds_read_b128 v[18:21], v0 offset:42752
	v_mfma_f32_16x16x32_bf16 v[14:17], v[118:121], v[6:9], v[14:17]
	v_mfma_f32_16x16x32_bf16 v[74:77], v[74:77], v[10:13], v[14:17]
	v_mfma_f32_16x16x32_bf16 v[14:17], v[66:69], v[2:5], 0
	v_mfma_f32_16x16x32_bf16 v[14:17], v[78:81], v[6:9], v[14:17]
	v_mfma_f32_16x16x32_bf16 v[78:81], v[110:113], v[10:13], v[14:17]
	v_mfma_f32_16x16x32_bf16 v[14:17], v[62:65], v[2:5], 0
	ds_read_b128 v[62:65], v0 offset:35840
	v_mfma_f32_16x16x32_bf16 v[14:17], v[70:73], v[6:9], v[14:17]
	v_mfma_f32_16x16x32_bf16 v[70:73], v[106:109], v[10:13], v[14:17]
	v_mfma_f32_16x16x32_bf16 v[2:5], v[58:61], v[2:5], 0
	ds_read_b128 v[58:61], v0 offset:38144
	s_nop 4
	ds_read_b128 v[14:17], v0 offset:35904
	v_mfma_f32_16x16x32_bf16 v[2:5], v[98:101], v[6:9], v[2:5]
	ds_read_b128 v[6:9], v0 offset:40512
	v_max_f32_e32 v98, v82, v82
	v_max3_f32 v99, v88, v89, v90
	v_mfma_f32_16x16x32_bf16 v[66:69], v[102:105], v[10:13], v[2:5]
	ds_read_b128 v[10:13], v0 offset:42816
	v_max3_f32 v100, v94, v95, v96
	s_nop 1
	ds_read_b128 v[2:5], v0 offset:38208
	v_max_f32_e32 v0, v83, v83
	v_max_f32_e32 v0, v98, v0
	v_max3_f32 v98, v85, v86, v87
	v_max3_f32 v0, v0, v84, v98
	v_max3_f32 v98, v91, v92, v93
	v_max3_f32 v0, v0, v99, v98
	v_max3_f32 v0, v0, v100, v97
	v_sub_f32_e32 v98, v0, v122
	v_mul_f32_e32 v98, 0x3e16c740, v98
	v_cmp_lt_f32_e32 vcc, s0, v98
	s_cbranch_vccz .LBB0_640
	v_mbcnt_hi_u32_b32 v98, -1, v203
	v_and_b32_e32 v100, 64, v98
	v_xor_b32_e32 v99, 16, v98
	v_add_u32_e32 v100, 64, v100
	v_cmp_lt_i32_e32 vcc, v99, v100
	s_nop 1
	v_cndmask_b32_e32 v99, v98, v99, vcc
	v_lshlrev_b32_e32 v99, 2, v99
	ds_bpermute_b32 v99, v99, v0
	v_max_f32_e32 v0, v0, v0
	s_waitcnt lgkmcnt(0)
	v_max_f32_e32 v99, v99, v99
	v_max_f32_e32 v0, v0, v99
	v_xor_b32_e32 v99, 32, v98
	v_cmp_lt_i32_e32 vcc, v99, v100
	s_nop 1
	v_cndmask_b32_e32 v98, v98, v99, vcc
	v_lshlrev_b32_e32 v98, 2, v98
	ds_bpermute_b32 v98, v98, v0
	s_waitcnt lgkmcnt(0)
	v_max3_f32 v98, v122, v0, v98
	v_sub_f32_e32 v0, v122, v98
	v_mul_f32_e32 v0, 0x3e16c740, v0
	v_exp_f32_e32 v0, v0
	v_mov_b32_e32 v122, v98
	v_mul_f32_e32 v124, v126, v0
	v_pk_mul_f32 v[44:45], v[44:45], v[0:1] op_sel_hi:[1,0]
	v_pk_mul_f32 v[42:43], v[42:43], v[0:1] op_sel_hi:[1,0]
	v_pk_mul_f32 v[48:49], v[48:49], v[0:1] op_sel_hi:[1,0]
	v_pk_mul_f32 v[46:47], v[46:47], v[0:1] op_sel_hi:[1,0]
	v_pk_mul_f32 v[52:53], v[52:53], v[0:1] op_sel_hi:[1,0]
	v_pk_mul_f32 v[50:51], v[50:51], v[0:1] op_sel_hi:[1,0]
	v_pk_mul_f32 v[56:57], v[56:57], v[0:1] op_sel_hi:[1,0]
	v_pk_mul_f32 v[54:55], v[54:55], v[0:1] op_sel_hi:[1,0]
	s_branch .LBB0_641

.LBB0_641:
	v_mul_f32_e32 v0, 0xbe16c740, v122
	s_mov_b32 s98, 0x3e16c740
	v_pk_fma_f32 v[82:83], v[82:83], s[98:99], v[0:1] op_sel_hi:[1,0,0]
	v_pk_fma_f32 v[84:85], v[84:85], s[98:99], v[0:1] op_sel_hi:[1,0,0]
	v_pk_fma_f32 v[86:87], v[86:87], s[98:99], v[0:1] op_sel_hi:[1,0,0]
	v_pk_fma_f32 v[88:89], v[88:89], s[98:99], v[0:1] op_sel_hi:[1,0,0]
	v_pk_fma_f32 v[90:91], v[90:91], s[98:99], v[0:1] op_sel_hi:[1,0,0]
	v_pk_fma_f32 v[92:93], v[92:93], s[98:99], v[0:1] op_sel_hi:[1,0,0]
	v_pk_fma_f32 v[94:95], v[94:95], s[98:99], v[0:1] op_sel_hi:[1,0,0]
	v_pk_fma_f32 v[96:97], v[96:97], s[98:99], v[0:1] op_sel_hi:[1,0,0]
	v_exp_f32_e32 v82, v82
	v_exp_f32_e32 v83, v83
	v_exp_f32_e32 v84, v84
	v_exp_f32_e32 v85, v85
	v_exp_f32_e32 v86, v86
	v_exp_f32_e32 v87, v87
	v_exp_f32_e32 v88, v88
	v_exp_f32_e32 v89, v89
	v_exp_f32_e32 v90, v90
	v_exp_f32_e32 v91, v91
	v_exp_f32_e32 v92, v92
	v_exp_f32_e32 v93, v93
	v_exp_f32_e32 v94, v94
	v_exp_f32_e32 v95, v95
	v_exp_f32_e32 v96, v96
	v_exp_f32_e32 v97, v97
	v_pk_add_f32 v[98:99], v[82:83], v[84:85]
	v_cvt_pk_bf16_f32 v82, v82, v83
	v_cvt_pk_bf16_f32 v83, v84, v85
	v_cvt_pk_bf16_f32 v84, v86, v87
	v_cvt_pk_bf16_f32 v85, v88, v89
	v_max_f32_e32 v0, v75, v75
	v_pk_add_f32 v[98:99], v[98:99], 0 op_sel_hi:[1,0]
	s_waitcnt lgkmcnt(5)
	v_mfma_f32_16x16x32_bf16 v[42:45], v[62:65], v[82:85], v[42:45]
	v_add_f32_e64 v100, v86, v88
	v_add_f32_e64 v101, v87, v89
	v_cvt_pk_bf16_f32 v86, v90, v91
	v_pk_add_f32 v[98:99], v[100:101], v[98:99]
	s_waitcnt lgkmcnt(4)
	v_mfma_f32_16x16x32_bf16 v[46:49], v[58:61], v[82:85], v[46:49]
	v_add_f32_e64 v100, v90, v92
	v_add_f32_e64 v101, v91, v93
	v_cvt_pk_bf16_f32 v87, v92, v93
	v_cvt_pk_bf16_f32 v88, v94, v95
	v_mfma_f32_16x16x32_bf16 v[50:53], v[22:25], v[82:85], v[50:53]
	v_cvt_pk_bf16_f32 v89, v96, v97
	v_pk_add_f32 v[98:99], v[100:101], v[98:99]
	v_pk_add_f32 v[100:101], v[94:95], v[96:97]
	v_mfma_f32_16x16x32_bf16 v[54:57], v[18:21], v[82:85], v[54:57]
	v_max_f32_e32 v82, v74, v74
	v_max_f32_e32 v0, v82, v0
	v_max3_f32 v82, v77, v78, v79
	v_max3_f32 v83, v80, v81, v70
	v_max3_f32 v0, v0, v76, v82
	v_max3_f32 v82, v71, v72, v73
	v_max3_f32 v84, v66, v67, v68
	v_max3_f32 v0, v0, v83, v82
	s_waitcnt lgkmcnt(3)
	v_mfma_f32_16x16x32_bf16 v[42:45], v[14:17], v[86:89], v[42:45]
	v_max3_f32 v82, v0, v84, v69
	v_pk_add_f32 v[98:99], v[100:101], v[98:99]
	v_sub_f32_e32 v0, v82, v123
	s_waitcnt lgkmcnt(0)
	v_mfma_f32_16x16x32_bf16 v[46:49], v[2:5], v[86:89], v[46:49]
	v_pk_add_f32 v[98:99], v[98:99], v[98:99] op_sel:[0,1] op_sel_hi:[1,0]
	v_mul_f32_e32 v0, 0x3e16c740, v0
	v_pk_add_f32 v[98:99], v[124:125], v[98:99]
	v_mfma_f32_16x16x32_bf16 v[50:53], v[6:9], v[86:89], v[50:53]
	v_cmp_lt_f32_e32 vcc, s0, v0
	v_mfma_f32_16x16x32_bf16 v[54:57], v[10:13], v[86:89], v[54:57]
	s_cbranch_vccz .LBB0_702
	v_mbcnt_hi_u32_b32 v0, -1, v203
	v_and_b32_e32 v83, 64, v0
	v_xor_b32_e32 v100, 16, v0
	v_add_u32_e32 v99, 64, v83
	v_cmp_lt_i32_e32 vcc, v100, v99
	v_xor_b32_e32 v101, 32, v0
	s_nop 0
	v_cndmask_b32_e32 v83, v0, v100, vcc
	v_lshlrev_b32_e32 v83, 2, v83
	ds_bpermute_b32 v83, v83, v82
	v_max_f32_e32 v82, v82, v82
	v_cmp_lt_i32_e32 vcc, v101, v99
	s_waitcnt lgkmcnt(0)
	v_max_f32_e32 v83, v83, v83
	v_max_f32_e32 v82, v82, v83
	v_cndmask_b32_e32 v83, v0, v101, vcc
	v_lshlrev_b32_e32 v83, 2, v83
	ds_bpermute_b32 v83, v83, v82
	s_waitcnt lgkmcnt(0)
	v_max3_f32 v103, v123, v82, v83
	v_sub_f32_e32 v82, v123, v103
	v_mul_f32_e32 v82, 0x3e16c740, v82
	v_exp_f32_e32 v82, v82
	s_nop 0
	v_mul_f32_e32 v102, v125, v82
	v_pk_mul_f32 v[96:97], v[28:29], v[82:83] op_sel_hi:[1,0]
	v_pk_mul_f32 v[94:95], v[26:27], v[82:83] op_sel_hi:[1,0]
	v_pk_mul_f32 v[92:93], v[32:33], v[82:83] op_sel_hi:[1,0]
	v_pk_mul_f32 v[90:91], v[30:31], v[82:83] op_sel_hi:[1,0]
	v_pk_mul_f32 v[88:89], v[36:37], v[82:83] op_sel_hi:[1,0]
	v_pk_mul_f32 v[86:87], v[34:35], v[82:83] op_sel_hi:[1,0]
	v_pk_mul_f32 v[84:85], v[40:41], v[82:83] op_sel_hi:[1,0]
	v_pk_mul_f32 v[82:83], v[38:39], v[82:83] op_sel_hi:[1,0]
	s_cbranch_execnz .LBB0_644

.LBB0_644:
	v_mul_f32_e32 v41, 0xbe16c740, v103
	s_mov_b32 s98, 0x3e16c740
	v_pk_fma_f32 v[66:67], v[66:67], s[98:99], v[40:41] op_sel:[0,0,1] op_sel_hi:[1,0,1]
	v_pk_fma_f32 v[68:69], v[68:69], s[98:99], v[40:41] op_sel:[0,0,1] op_sel_hi:[1,0,1]
	v_pk_fma_f32 v[70:71], v[70:71], s[98:99], v[40:41] op_sel:[0,0,1] op_sel_hi:[1,0,1]
	v_pk_fma_f32 v[72:73], v[72:73], s[98:99], v[40:41] op_sel:[0,0,1] op_sel_hi:[1,0,1]
	v_pk_fma_f32 v[74:75], v[74:75], s[98:99], v[40:41] op_sel:[0,0,1] op_sel_hi:[1,0,1]
	v_pk_fma_f32 v[76:77], v[76:77], s[98:99], v[40:41] op_sel:[0,0,1] op_sel_hi:[1,0,1]
	v_pk_fma_f32 v[78:79], v[78:79], s[98:99], v[40:41] op_sel:[0,0,1] op_sel_hi:[1,0,1]
	v_pk_fma_f32 v[80:81], v[80:81], s[98:99], v[40:41] op_sel:[0,0,1] op_sel_hi:[1,0,1]
	v_exp_f32_e32 v26, v74
	v_exp_f32_e32 v27, v75
	v_exp_f32_e32 v28, v76
	v_exp_f32_e32 v29, v77
	v_exp_f32_e32 v30, v78
	v_exp_f32_e32 v31, v79
	v_exp_f32_e32 v32, v80
	v_exp_f32_e32 v33, v81
	v_exp_f32_e32 v34, v70
	v_exp_f32_e32 v35, v71
	v_exp_f32_e32 v36, v72
	v_exp_f32_e32 v37, v73
	v_exp_f32_e32 v38, v66
	v_exp_f32_e32 v39, v67
	v_exp_f32_e32 v40, v68
	v_exp_f32_e32 v41, v69
	v_pk_add_f32 v[66:67], v[26:27], v[28:29]
	v_pk_add_f32 v[68:69], v[30:31], v[32:33]
	v_pk_add_f32 v[66:67], v[66:67], 0 op_sel_hi:[1,0]
	v_cvt_pk_bf16_f32 v26, v26, v27
	v_pk_add_f32 v[66:67], v[68:69], v[66:67]
	v_pk_add_f32 v[68:69], v[34:35], v[36:37]
	v_cvt_pk_bf16_f32 v27, v28, v29
	v_cvt_pk_bf16_f32 v28, v30, v31
	v_cvt_pk_bf16_f32 v29, v32, v33
	v_pk_add_f32 v[66:67], v[68:69], v[66:67]
	v_pk_add_f32 v[68:69], v[38:39], v[40:41]
	v_cvt_pk_bf16_f32 v30, v34, v35
	v_cvt_pk_bf16_f32 v31, v36, v37
	v_cvt_pk_bf16_f32 v32, v38, v39
	v_cvt_pk_bf16_f32 v33, v40, v41
	v_mfma_f32_16x16x32_bf16 v[34:37], v[62:65], v[26:29], v[94:97]
	v_cmp_lt_i32_e32 vcc, v100, v99
	s_lshl_b64 s[0:1], s[10:11], 11
	v_readlane_b32 s4, v254, 33
	v_mfma_f32_16x16x32_bf16 v[38:41], v[58:61], v[26:29], v[90:93]
	v_readlane_b32 s5, v254, 34
	s_add_u32 s0, s4, s0
	s_addc_u32 s1, s5, s1
	v_mfma_f32_16x16x32_bf16 v[22:25], v[22:25], v[26:29], v[86:89]
	s_add_u32 s4, s0, s12
	s_addc_u32 s5, s1, 0
	v_mfma_f32_16x16x32_bf16 v[26:29], v[18:21], v[26:29], v[82:85]
	s_barrier
	v_pk_add_f32 v[66:67], v[68:69], v[66:67]
	v_mfma_f32_16x16x32_bf16 v[18:21], v[2:5], v[30:33], v[38:41]
	v_add_f32_e32 v66, v66, v67
	v_add_f32_e32 v66, v102, v66
	v_mfma_f32_16x16x32_bf16 v[2:5], v[10:13], v[30:33], v[26:29]
	v_cndmask_b32_e32 v10, v0, v100, vcc
	v_cmp_lt_i32_e32 vcc, v101, v99
	s_nop 0
	v_lshlrev_b32_e32 v26, 2, v10
	v_cndmask_b32_e32 v0, v0, v101, vcc
	v_lshlrev_b32_e32 v27, 2, v0
	ds_bpermute_b32 v0, v26, v98
	v_mfma_f32_16x16x32_bf16 v[6:9], v[6:9], v[30:33], v[22:25]
	s_waitcnt lgkmcnt(0)
	v_add_f32_e32 v0, v98, v0
	ds_bpermute_b32 v10, v27, v0
	v_mfma_f32_16x16x32_bf16 v[14:17], v[14:17], v[30:33], v[34:37]
	s_waitcnt lgkmcnt(0)
	v_add_f32_e32 v0, v0, v10
	v_div_scale_f32 v10, s[0:1], v0, v0, 1.0
	v_rcp_f32_e32 v11, v10
	s_nop 0
	v_fma_f32 v12, -v10, v11, 1.0
	v_fmac_f32_e32 v11, v12, v11
	v_div_scale_f32 v12, vcc, 1.0, v0, 1.0
	v_mul_f32_e32 v13, v12, v11
	v_fma_f32 v22, -v10, v13, v12
	v_fmac_f32_e32 v13, v22, v11
	v_fma_f32 v10, -v10, v13, v12
	v_div_fmas_f32 v10, v10, v11, v13
	v_div_fixup_f32 v10, v10, v0, 1.0
	v_lshlrev_b64 v[12:13], 11, v[148:149]
	v_lshl_add_u64 v[12:13], s[4:5], 0, v[12:13]
	v_lshlrev_b32_e32 v0, 3, v186
	v_pk_mul_f32 v[22:23], v[44:45], v[10:11] op_sel_hi:[1,0]
	v_pk_mul_f32 v[24:25], v[42:43], v[10:11] op_sel_hi:[1,0]
	v_lshl_add_u64 v[12:13], v[12:13], 0, v[0:1]
	v_cvt_pk_bf16_f32 v24, v24, v25
	v_cvt_pk_bf16_f32 v25, v22, v23
	global_store_dwordx2 v[12:13], v[24:25], off
	v_pk_mul_f32 v[22:23], v[48:49], v[10:11] op_sel_hi:[1,0]
	v_pk_mul_f32 v[24:25], v[46:47], v[10:11] op_sel_hi:[1,0]
	s_nop 0
	v_cvt_pk_bf16_f32 v24, v24, v25
	v_cvt_pk_bf16_f32 v25, v22, v23
	global_store_dwordx2 v[12:13], v[24:25], off offset:32
	v_pk_mul_f32 v[22:23], v[52:53], v[10:11] op_sel_hi:[1,0]
	v_pk_mul_f32 v[24:25], v[50:51], v[10:11] op_sel_hi:[1,0]
	s_nop 0
	v_cvt_pk_bf16_f32 v24, v24, v25
	v_cvt_pk_bf16_f32 v25, v22, v23
	v_pk_mul_f32 v[22:23], v[56:57], v[10:11] op_sel_hi:[1,0]
	v_pk_mul_f32 v[10:11], v[54:55], v[10:11] op_sel_hi:[1,0]
	global_store_dwordx2 v[12:13], v[24:25], off offset:64
	v_cvt_pk_bf16_f32 v10, v10, v11
	v_cvt_pk_bf16_f32 v11, v22, v23
	global_store_dwordx2 v[12:13], v[10:11], off offset:96
	ds_bpermute_b32 v10, v26, v66
	s_waitcnt lgkmcnt(0)
	v_add_f32_e32 v10, v66, v10
	ds_bpermute_b32 v11, v27, v10
	s_waitcnt lgkmcnt(0)
	v_add_f32_e32 v10, v10, v11
	v_div_scale_f32 v11, s[0:1], v10, v10, 1.0
	v_rcp_f32_e32 v12, v11
	s_nop 0
	v_fma_f32 v13, -v11, v12, 1.0
	v_fmac_f32_e32 v12, v13, v12
	v_div_scale_f32 v13, vcc, 1.0, v10, 1.0
	v_mul_f32_e32 v22, v13, v12
	v_fma_f32 v23, -v11, v22, v13
	v_fmac_f32_e32 v22, v23, v12
	v_fma_f32 v11, -v11, v22, v13
	v_div_fmas_f32 v11, v11, v12, v22
	v_div_fixup_f32 v10, v11, v10, 1.0
	v_lshlrev_b64 v[12:13], 11, v[146:147]
	v_lshl_add_u64 v[12:13], s[4:5], 0, v[12:13]
	v_pk_mul_f32 v[16:17], v[16:17], v[10:11] op_sel_hi:[1,0]
	v_pk_mul_f32 v[14:15], v[14:15], v[10:11] op_sel_hi:[1,0]
	v_lshl_add_u64 v[12:13], v[12:13], 0, v[0:1]
	v_cvt_pk_bf16_f32 v14, v14, v15
	v_cvt_pk_bf16_f32 v15, v16, v17
	global_store_dwordx2 v[12:13], v[14:15], off
	v_pk_mul_f32 v[14:15], v[20:21], v[10:11] op_sel_hi:[1,0]
	v_pk_mul_f32 v[16:17], v[18:19], v[10:11] op_sel_hi:[1,0]
	v_pk_mul_f32 v[8:9], v[8:9], v[10:11] op_sel_hi:[1,0]
	v_pk_mul_f32 v[6:7], v[6:7], v[10:11] op_sel_hi:[1,0]
	v_pk_mul_f32 v[4:5], v[4:5], v[10:11] op_sel_hi:[1,0]
	v_pk_mul_f32 v[2:3], v[2:3], v[10:11] op_sel_hi:[1,0]
	v_cvt_pk_bf16_f32 v16, v16, v17
	v_cvt_pk_bf16_f32 v17, v14, v15
	v_cvt_pk_bf16_f32 v6, v6, v7
	v_cvt_pk_bf16_f32 v7, v8, v9
	v_cvt_pk_bf16_f32 v2, v2, v3
	v_cvt_pk_bf16_f32 v3, v4, v5
	global_store_dwordx2 v[12:13], v[16:17], off offset:32
	global_store_dwordx2 v[12:13], v[6:7], off offset:64
	global_store_dwordx2 v[12:13], v[2:3], off offset:96
